# attention tile loop: mask words prefetched one tile ahead, top-of-tile wait no longer drains K/V loads (on top of S3 waits)
# speedup vs baseline: 1.0031x; 1.0031x over previous
; #define LAS __attribute__((address_space(3)))
;     template <class T> __device__ __forceinline__ T* w(size_t off) const { return (T*)(pp->ws + off); }
; template <class T> __device__ __forceinline__ LAS T* opq(LAS T* p) { asm volatile("" : "+v"(p)); return p; }
; #define ATT_LOAD(tile) do { _Pragma("unroll") for (int _i = 0; _i < 2; ++_i) { const size_t _o = (size_t)((tile) * 64 + sk0 + 32 * _i) * 256 + sseg * 8; kr[_i] = *(const u32x4*)(KC + _o); vr[_i] = *(const u32x4*)(VC + _o); } } while (0)
; __device__ __forceinline__ void dsa_attn_unit(const Ctx& c, int l, int b, int kvh, int qb64) {
;     const int lane = c.lane, wave = c.wave, n = lane & 31, hf = lane >> 5;
;     const int g = wave >> 1, qh = wave & 1;
;     const int tq = qb64 * 64 + 32 * qh + n, row = b * 2048 + tq, hq = kvh * 4 + g;
;     LAS unsigned char* Kt = opq(c.lds);
;     LAS unsigned char* VT = opq(c.lds + 2 * 64 * 272);
;     const bf16* KC = c.w<bf16>(WS_KC) + (size_t)(b * 2048) * 256 + kvh * 128;
;     const bf16* VC = c.w<bf16>(WS_VC) + (size_t)(b * 2048) * 256 + kvh * 128;
;     const unsigned* mrow = c.w<unsigned>(WS_MASK) + (size_t)row * 64;
;     bf16x8 Qf[8];
;     { const bf16* qp = c.w<bf16>(WS_QC) + (size_t)row * 1024 + hq * 128 + 8 * hf;
; #pragma unroll
;       for (int ks = 0; ks < 8; ++ks) Qf[ks] = *(const bf16x8*)(qp + 16 * ks); }
;     f32x16 O[4];
; #pragma unroll
;     for (int mt = 0; mt < 4; ++mt)
; #pragma unroll
;         for (int v = 0; v < 16; ++v) O[mt][v] = 0.f;
;     float m_run = -1e30f, l_run = 0.f;
;     const int ntile = qb64 + 1;
;     const int sk0 = c.tid >> 4, sseg = c.tid & 15;
;     u32x4 kr[2], vr[2];
;     ...
;     __syncthreads();
;     ATT_LOAD(0); ATT_STORE(0);
.LBB0_1434:
	s_andn2_b64 vcc, exec, s[0:1]
	s_cbranch_vccnz .LBB0_1355
	s_cmp_gt_i32 s87, 31
	s_mov_b64 s[0:1], -1
	s_cbranch_scc0 .LBB0_1468
	s_cmpk_gt_u32 s87, 0x9f
	s_cbranch_scc0 .LBB0_1452
	s_add_i32 s0, s87, 0xffffff60
	s_lshr_b32 s4, s0, 3
	s_sub_i32 s6, 31, s4
	s_lshl_b32 s0, s6, 6
	v_mov_b32_e32 v12, v161
	v_mov_b32_e32 v163, s81
	s_or_b32 s5, s0, s39
	s_load_dwordx2 s[0:1], s[90:91], 0xc0
	s_and_b32 s2, s87, 3
	s_lshl_b32 s7, s2, 11
	s_bfe_u32 s3, s87, 0x10002
	s_or_b32 s5, s5, s7
	s_lshl_b32 s18, s2, 20
	v_and_b32_e32 v10, 31, v164
	s_waitcnt lgkmcnt(0)
	s_add_u32 s2, s0, s18
	v_or_b32_e32 v166, s5, v10
	s_addc_u32 s7, s1, 0
	s_lshl_b32 s5, s3, 8
	s_add_u32 s58, s2, s5
	s_addc_u32 s7, s7, 0
	s_add_u32 s8, s58, 0x30100000
	s_addc_u32 s9, s7, 0
	s_lshl_b32 s2, s3, 9
	v_ashrrev_i32_e32 v11, 5, v164
	v_lshlrev_b32_e32 v0, 11, v166
	v_mov_b32_e32 v1, v161
	s_add_i32 s2, s2, s68
	v_lshl_add_u64 v[0:1], s[0:1], 0, v[0:1]
	s_ashr_i32 s3, s2, 31
	v_lshlrev_b32_e32 v2, 3, v11
	v_lshl_add_u64 v[0:1], s[2:3], 1, v[0:1]
	v_ashrrev_i32_e32 v3, 31, v2
	v_lshl_add_u64 v[0:1], v[2:3], 1, v[0:1]
	s_mov_b32 s59, 0x2eb00000
	v_lshl_add_u64 v[2:3], v[0:1], 0, s[46:47]
	v_add_co_u32_e32 v0, vcc, s59, v0
	v_and_b32_e32 v13, 15, v164
	s_nop 0
	v_addc_co_u32_e32 v1, vcc, 0, v1, vcc
	global_load_dwordx4 v[80:83], v[2:3], off offset:32
	global_load_dwordx4 v[84:87], v[2:3], off offset:64
	global_load_dwordx4 v[88:91], v[2:3], off offset:96
	global_load_dwordx4 v[92:95], v[2:3], off offset:128
	global_load_dwordx4 v[96:99], v[2:3], off offset:160
	global_load_dwordx4 v[100:103], v[2:3], off offset:192
	global_load_dwordx4 v[104:107], v[0:1], off
	global_load_dwordx4 v[108:111], v[2:3], off offset:224
	v_ashrrev_i32_e32 v0, 4, v162
	v_ashrrev_i32_e32 v1, 31, v0
	s_add_u32 s58, s58, 0x2fc00000
	v_lshlrev_b32_e32 v14, 4, v13
	v_lshlrev_b64 v[2:3], 9, v[0:1]
	s_addc_u32 s59, s7, 0
	v_or_b32_e32 v4, v2, v14
	v_mov_b32_e32 v5, v3
	v_lshl_add_u64 v[6:7], s[58:59], 0, v[4:5]
	v_lshl_add_u64 v[4:5], s[8:9], 0, v[4:5]
	s_barrier
	global_load_dwordx4 v[112:115], v[6:7], off
	global_load_dwordx4 v[116:119], v[4:5], off
	v_add_u32_e32 v4, 32, v0
	v_ashrrev_i32_e32 v5, 31, v4
	v_lshlrev_b64 v[6:7], 9, v[4:5]
	v_or_b32_e32 v6, v6, v14
	v_lshl_add_u64 v[8:9], s[58:59], 0, v[6:7]
	v_lshl_add_u64 v[6:7], s[8:9], 0, v[6:7]
	global_load_dwordx4 v[120:123], v[8:9], off
	global_load_dwordx4 v[124:127], v[6:7], off
	s_movk_i32 s8, 0x110
	s_movk_i32 s9, 0x500
	v_lshlrev_b32_e32 v1, 2, v13
	v_mul_lo_u32 v165, v0, s8
	v_add_u32_e32 v169, v12, v14
	v_mad_u32_u24 v182, v13, s9, v163
	v_xor_b32_e32 v184, v4, v1
	v_xor_b32_e32 v183, v1, v0
	v_add_u32_e32 v0, v169, v165
	v_lshl_add_u32 v4, v184, 1, v182
	v_lshl_add_u32 v1, v183, 1, v182
	v_lshlrev_b32_e32 v168, 2, v11
	s_movk_i32 s8, 0xa0
	v_lshl_add_u64 v[172:173], s[18:19], 0, v[2:3]
	v_mov_b32_e32 v32, v161
	v_mov_b32_e32 v33, v161
	v_mov_b32_e32 v46, v161
	v_mov_b32_e32 v47, v161
	v_lshlrev_b32_e32 v160, 8, v166
	v_lshl_add_u32 v185, v11, 4, v12
	v_mul_u32_u24_e32 v187, 0x110, v10
	v_mul_u32_u24_e32 v188, 0xa0, v10
	v_mad_u32_u24 v210, v10, s8, v179
	v_or3_b32 v172, v172, s5, v14
	v_mov_b32_e32 v34, v161
	v_mov_b32_e32 v35, v161
	v_mov_b32_e32 v36, v161
	v_mov_b32_e32 v37, v161
	v_mov_b32_e32 v38, v161
	v_mov_b32_e32 v39, v161
	v_mov_b32_e32 v40, v161
	v_mov_b32_e32 v41, v161
	v_mov_b32_e32 v42, v161
	v_mov_b32_e32 v43, v161
	v_mov_b32_e32 v44, v161
	v_mov_b32_e32 v45, v161
	v_mov_b64_e32 v[62:63], v[46:47]
	v_mov_b64_e32 v[16:17], v[32:33]
	s_mov_b32 s7, 0
	v_mov_b64_e32 v[170:171], v[160:161]
	v_lshlrev_b32_e32 v160, 10, v166
	s_sub_i32 s8, 32, s4
	v_mov_b32_e32 v192, 0
	v_mov_b32_e32 v223, 0xf149f2ca
	v_mov_b64_e32 v[60:61], v[44:45]
	v_mov_b64_e32 v[58:59], v[42:43]
	s_waitcnt vmcnt(3)
	ds_write_b128 v0, v[112:115]
	s_waitcnt vmcnt(2)
	ds_write_b16 v1, v116
	ds_write_b16_d16_hi v1, v116 offset:160
	ds_write_b16 v1, v117 offset:320
	ds_write_b16_d16_hi v1, v117 offset:480
	ds_write_b16 v1, v118 offset:640
	ds_write_b16_d16_hi v1, v118 offset:800
	ds_write_b16 v1, v119 offset:960
	ds_write_b16_d16_hi v1, v119 offset:1120
	s_waitcnt vmcnt(1)
	ds_write_b128 v0, v[120:123] offset:8704
	s_waitcnt vmcnt(0)
; #define LAS __attribute__((address_space(3)))
; #define ATT_LOAD(tile) do { _Pragma("unroll") for (int _i = 0; _i < 2; ++_i) { const size_t _o = (size_t)((tile) * 64 + sk0 + 32 * _i) * 256 + sseg * 8; kr[_i] = *(const u32x4*)(KC + _o); vr[_i] = *(const u32x4*)(VC + _o); } } while (0)
; __device__ __forceinline__ void dsa_attn_unit(const Ctx& c, int l, int b, int kvh, int qb64) {
;     ...
;     f32x16 O[4];
; #pragma unroll
;     for (int mt = 0; mt < 4; ++mt)
; #pragma unroll
;         for (int v = 0; v < 16; ++v) O[mt][v] = 0.f;
;     float m_run = -1e30f, l_run = 0.f;
;     const int ntile = qb64 + 1;
;     const int sk0 = c.tid >> 4, sseg = c.tid & 15;
;     u32x4 kr[2], vr[2];
;     ...
;     __syncthreads();
;     ATT_LOAD(0); ATT_STORE(0);
;     __syncthreads();
; #pragma unroll 1
;     for (int it = 0; it < ntile; ++it) {
;         const int bi = it & 1;
;         if (it + 1 < ntile) ATT_LOAD(it + 1);
;         const unsigned mw[2] = {mrow[2 * it], mrow[2 * it + 1]};
; #pragma unroll
;         for (int sub = 0; sub < 2; ++sub) {
;             const unsigned mwd = mw[sub];
;             if (__ballot(mwd != 0u) == 0ull) continue;
;             f32x16 acc;
; #pragma unroll
;             for (int v = 0; v < 16; ++v) acc[v] = 0.f;
;             const LAS unsigned char* kp = Kt + bi * 17408 + (sub * 32 + n) * 272 + hf * 16;
;             bf16x8 Kf[8];
; #pragma unroll
;             for (int ks = 0; ks < 8; ++ks) Kf[ks] = *(const LAS bf16x8*)(kp + ks * 32);
;             __builtin_amdgcn_sched_barrier(0);
; #pragma unroll
;             for (int ks = 0; ks < 8; ++ks) acc = __builtin_amdgcn_mfma_f32_32x32x16_bf16(Kf[ks], Qf[ks], acc, 0, 0, 0);
;             bf16x8 Vf[8];
; #pragma unroll
;             for (int mt = 0; mt < 4; ++mt)
; #pragma unroll
;                 for (int s2 = 0; s2 < 2; ++s2) {
;                     const int xr = 4 * (4 * mt + (n >> 3)), kb = sub * 32 + 16 * s2 + 4 * hf;
;                     const LAS unsigned char* vrow = VT + bi * 20480 + (32 * mt + n) * 160;
;                     const u32x2 lo = *(const LAS u32x2*)(vrow + (kb ^ xr) * 2), hi = *(const LAS u32x2*)(vrow + ((kb + 8) ^ xr) * 2);
;     ...
;         if (it + 1 < ntile) ATT_STORE(bi ^ 1);
;         __syncthreads();
;     }
	ds_write_b16 v4, v124
	ds_write_b16_d16_hi v4, v124 offset:160
	ds_write_b16 v4, v125 offset:320
	ds_write_b16_d16_hi v4, v125 offset:480
	ds_write_b16 v4, v126 offset:640
	ds_write_b16_d16_hi v4, v126 offset:800
	ds_write_b16 v4, v127 offset:960
	ds_write_b16_d16_hi v4, v127 offset:1120
	v_lshrrev_b32_e32 v0, 1, v164
	v_lshlrev_b32_e32 v4, 2, v164
	v_xor_b32_e32 v186, 0x80, v4
	v_bitop3_b32 v4, v168, v0, 12 bitop3:0x78
	v_lshlrev_b32_e32 v189, 1, v4
	v_add_u32_e32 v4, 8, v168
	v_bitop3_b32 v5, v4, v0, 12 bitop3:0x78
	v_lshlrev_b32_e32 v190, 1, v5
	v_add_u32_e32 v5, 16, v168
	v_bitop3_b32 v6, v5, v0, 12 bitop3:0x78
	v_lshlrev_b32_e32 v191, 1, v6
	v_add_u32_e32 v6, 24, v168
	v_and_b32_e32 v1, 12, v0
	v_bitop3_b32 v7, v6, v0, 12 bitop3:0x78
	v_lshlrev_b32_e32 v193, 1, v7
	v_bitop3_b32 v7, v1, v168, 16 bitop3:0x36
	v_lshlrev_b32_e32 v194, 1, v7
	v_bitop3_b32 v7, v4, v1, 16 bitop3:0x1e
	v_lshlrev_b32_e32 v195, 1, v7
	v_bitop3_b32 v7, v5, v1, 16 bitop3:0x1e
	v_lshlrev_b32_e32 v196, 1, v7
	v_bitop3_b32 v7, v6, v1, 16 bitop3:0x1e
	v_lshlrev_b32_e32 v197, 1, v7
	v_bitop3_b32 v7, v1, v168, 32 bitop3:0x36
	v_lshlrev_b32_e32 v198, 1, v7
	v_bitop3_b32 v7, v4, v1, 32 bitop3:0x1e
	v_bitop3_b32 v4, v4, v1, 48 bitop3:0x1e
	v_lshlrev_b32_e32 v203, 1, v4
	v_bitop3_b32 v4, v5, v1, 48 bitop3:0x1e
	v_lshlrev_b32_e32 v204, 1, v4
	v_bitop3_b32 v4, v6, v1, 48 bitop3:0x1e
	v_lshlrev_b32_e32 v205, 1, v4
	v_add_u32_e32 v4, 32, v168
	v_lshlrev_b32_e32 v199, 1, v7
	v_bitop3_b32 v7, v5, v1, 32 bitop3:0x1e
	v_bitop3_b32 v5, v4, v0, 12 bitop3:0x78
	v_lshlrev_b32_e32 v206, 1, v5
	v_add_u32_e32 v5, 40, v168
	v_lshlrev_b32_e32 v200, 1, v7
	v_bitop3_b32 v7, v6, v1, 32 bitop3:0x1e
	v_bitop3_b32 v6, v5, v0, 12 bitop3:0x78
	v_lshlrev_b32_e32 v201, 1, v7
	v_bitop3_b32 v7, v1, v168, 48 bitop3:0x36
	v_lshlrev_b32_e32 v207, 1, v6
	v_add_u32_e32 v6, 48, v168
	v_lshlrev_b32_e32 v202, 1, v7
	v_bitop3_b32 v7, v6, v0, 12 bitop3:0x78
	v_lshlrev_b32_e32 v208, 1, v7
	v_add_u32_e32 v7, 56, v168
	v_bitop3_b32 v0, v7, v0, 12 bitop3:0x78
	v_lshlrev_b32_e32 v209, 1, v0
	v_bitop3_b32 v0, v4, v1, 16 bitop3:0x1e
	v_lshlrev_b32_e32 v211, 1, v0
	v_bitop3_b32 v0, v5, v1, 16 bitop3:0x1e
	v_lshlrev_b32_e32 v212, 1, v0
	v_bitop3_b32 v0, v6, v1, 16 bitop3:0x1e
	v_lshlrev_b32_e32 v213, 1, v0
	v_bitop3_b32 v0, v7, v1, 16 bitop3:0x1e
	v_lshlrev_b32_e32 v214, 1, v0
	v_bitop3_b32 v0, v4, v1, 32 bitop3:0x1e
	v_lshlrev_b32_e32 v215, 1, v0
	v_bitop3_b32 v0, v5, v1, 32 bitop3:0x1e
	v_lshlrev_b32_e32 v216, 1, v0
	v_bitop3_b32 v0, v6, v1, 32 bitop3:0x1e
	v_lshlrev_b32_e32 v217, 1, v0
	v_bitop3_b32 v0, v7, v1, 32 bitop3:0x1e
	v_lshlrev_b32_e32 v218, 1, v0
	v_bitop3_b32 v0, v4, v1, 48 bitop3:0x1e
	v_lshlrev_b32_e32 v219, 1, v0
	v_bitop3_b32 v0, v5, v1, 48 bitop3:0x1e
	v_lshlrev_b32_e32 v220, 1, v0
	v_bitop3_b32 v0, v6, v1, 48 bitop3:0x1e
	v_lshlrev_b32_e32 v221, 1, v0
	v_bitop3_b32 v0, v7, v1, 48 bitop3:0x1e
	v_lshlrev_b32_e32 v222, 1, v0
	v_mov_b64_e32 v[0:1], v[32:33]
	v_mov_b64_e32 v[56:57], v[40:41]
	v_mov_b64_e32 v[54:55], v[38:39]
	v_mov_b64_e32 v[52:53], v[36:37]
	v_mov_b64_e32 v[50:51], v[34:35]
	v_mov_b64_e32 v[48:49], v[32:33]
	v_mov_b64_e32 v[18:19], v[34:35]
	v_mov_b64_e32 v[20:21], v[36:37]
	v_mov_b64_e32 v[22:23], v[38:39]
	v_mov_b64_e32 v[24:25], v[40:41]
	v_mov_b64_e32 v[26:27], v[42:43]
	v_mov_b64_e32 v[28:29], v[44:45]
	v_mov_b64_e32 v[30:31], v[46:47]
	v_mov_b64_e32 v[2:3], v[34:35]
	v_mov_b64_e32 v[4:5], v[36:37]
	v_mov_b64_e32 v[6:7], v[38:39]
	v_mov_b64_e32 v[8:9], v[40:41]
	v_mov_b64_e32 v[10:11], v[42:43]
	v_mov_b64_e32 v[12:13], v[44:45]
	v_mov_b64_e32 v[14:15], v[46:47]
	s_waitcnt lgkmcnt(0)
	s_barrier
	v_lshl_add_u64 v[64:65], s[0:1], 0, v[170:171]
	v_add_co_u32_e32 v64, vcc, 0x4b800000, v64
	s_nop 1
	v_addc_co_u32_e32 v65, vcc, 0, v65, vcc
	global_load_dwordx2 v[174:175], v[64:65], off
	s_branch .LBB0_1440
.LBB0_1438:
	s_waitcnt vmcnt(0)
	s_xor_b32 s4, s9, 1
	s_mul_i32 s5, s4, 0x4400
	s_mulk_i32 s4, 0x5000
	v_add_u32_e32 v64, s4, v182
	v_add3_u32 v65, v169, s5, v165
	v_lshl_add_u32 v66, v183, 1, v64
	v_lshl_add_u32 v64, v184, 1, v64
	ds_write_b128 v65, v[112:115]
	ds_write_b16 v66, v116
	ds_write_b16_d16_hi v66, v116 offset:160
	ds_write_b16 v66, v117 offset:320
	ds_write_b16_d16_hi v66, v117 offset:480
	ds_write_b16 v66, v118 offset:640
	ds_write_b16_d16_hi v66, v118 offset:800
	ds_write_b16 v66, v119 offset:960
	ds_write_b16_d16_hi v66, v119 offset:1120
	ds_write_b128 v65, v[120:123] offset:8704
	ds_write_b16 v64, v124
	ds_write_b16_d16_hi v64, v124 offset:160
	ds_write_b16 v64, v125 offset:320
	ds_write_b16_d16_hi v64, v125 offset:480
	ds_write_b16 v64, v126 offset:640
	ds_write_b16_d16_hi v64, v126 offset:800
	ds_write_b16 v64, v127 offset:960
	ds_write_b16_d16_hi v64, v127 offset:1120
.LBB0_1439:
	s_waitcnt vmcnt(0)
	v_mov_b32_e32 v174, v236
	v_mov_b32_e32 v175, v237
	s_add_i32 s7, s7, 1
	v_lshl_add_u64 v[170:171], v[170:171], 0, 8
	s_cmp_lg_u32 s8, s7
	v_lshl_add_u64 v[172:173], v[172:173], 0, s[48:49]
	s_waitcnt lgkmcnt(0)
	s_barrier
	s_cbranch_scc0 .LBB0_1451
.LBB0_1440:
	v_lshl_add_u64 v[64:65], s[0:1], 0, v[170:171]
	v_add_co_u32_e32 v64, vcc, 0x4b800000, v64
	s_nop 1
	v_addc_co_u32_e32 v65, vcc, 0, v65, vcc
	global_load_dwordx2 v[236:237], v[64:65], off offset:8
	s_cmp_lt_u32 s7, s6
	s_cselect_b64 s[4:5], -1, 0
	s_cmp_ge_u32 s7, s6
	s_cbranch_scc1 .La0_nonext
	v_lshl_add_u64 v[64:65], s[0:1], 0, v[172:173]
	v_add_co_u32_e32 v66, vcc, 0x2fc08000, v64
	s_nop 1
	v_addc_co_u32_e32 v67, vcc, 0, v65, vcc
	v_add_co_u32_e32 v68, vcc, 0x30108000, v64
	s_nop 1
	v_addc_co_u32_e32 v69, vcc, 0, v65, vcc
	global_load_dwordx4 v[112:115], v[66:67], off
	global_load_dwordx4 v[116:119], v[68:69], off
	v_add_co_u32_e32 v66, vcc, 0x2fc0c000, v64
	s_nop 1
	v_addc_co_u32_e32 v67, vcc, 0, v65, vcc
	v_add_co_u32_e32 v64, vcc, 0x3010c000, v64
	s_nop 1
	v_addc_co_u32_e32 v65, vcc, 0, v65, vcc
	global_load_dwordx4 v[120:123], v[66:67], off
	global_load_dwordx4 v[124:127], v[64:65], off
	s_waitcnt vmcnt(5)
	s_branch .LBB0_1442

; #define LAS __attribute__((address_space(3)))
; __device__ __forceinline__ void dsa_attn_unit(const Ctx& c, int l, int b, int kvh, int qb64) {
;     ...
;             const unsigned mwd = mw[sub];
;             if (__ballot(mwd != 0u) == 0ull) continue;
;             f32x16 acc;
; #pragma unroll
;             for (int v = 0; v < 16; ++v) acc[v] = 0.f;
;             const LAS unsigned char* kp = Kt + bi * 17408 + (sub * 32 + n) * 272 + hf * 16;
;             bf16x8 Kf[8];
; #pragma unroll
;             for (int ks = 0; ks < 8; ++ks) Kf[ks] = *(const LAS bf16x8*)(kp + ks * 32);
;             __builtin_amdgcn_sched_barrier(0);
; #pragma unroll
;             for (int ks = 0; ks < 8; ++ks) acc = __builtin_amdgcn_mfma_f32_32x32x16_bf16(Kf[ks], Qf[ks], acc, 0, 0, 0);
;             bf16x8 Vf[8];
; #pragma unroll
;             for (int mt = 0; mt < 4; ++mt)
; #pragma unroll
;                 for (int s2 = 0; s2 < 2; ++s2) {
;                     const int xr = 4 * (4 * mt + (n >> 3)), kb = sub * 32 + 16 * s2 + 4 * hf;
;                     const LAS unsigned char* vrow = VT + bi * 20480 + (32 * mt + n) * 160;
;                     const u32x2 lo = *(const LAS u32x2*)(vrow + (kb ^ xr) * 2), hi = *(const LAS u32x2*)(vrow + ((kb + 8) ^ xr) * 2);
;                     const u32x4 t = {lo.x, lo.y, hi.x, hi.y};
;                     Vf[mt * 2 + s2] = __builtin_bit_cast(bf16x8, t);
;                 }
;             __builtin_amdgcn_sched_barrier(0);
;             const unsigned wsh = mwd >> (4 * hf);
;             float mx = -INFINITY;
; #pragma unroll
;             for (int v = 0; v < 16; ++v) { const bool selv = (wsh >> ((v & 3) + 8 * (v >> 2))) & 1u; acc[v] = selv ? acc[v] * 0.12751743f : -INFINITY; mx = fmaxf(mx, acc[v]); }
;             mx = fmaxf(mx, lane_get(mx, lane ^ 32));
;             const float m_new = fmaxf(m_run, mx);
;             const float alpha = __builtin_amdgcn_exp2f(m_run - m_new);
;             float rs = 0.f;
; #pragma unroll
;             for (int v = 0; v < 16; ++v) { acc[v] = __builtin_amdgcn_exp2f(acc[v] - m_new); rs += acc[v]; }
;             rs += lane_get(rs, lane ^ 32);
;             l_run = l_run * alpha + rs; m_run = m_new;
;             if (__ballot(alpha != 1.0f) != 0ull) {
.LBB0_1442:
	s_and_b32 s9, s7, 1
	s_mul_i32 s18, s9, 0x4400
	s_mul_i32 s58, s9, 0x5000
	v_add_u32_e32 v64, s18, v185
	v_add_u32_e32 v225, s58, v163
	v_add_u32_e32 v226, v64, v187
	v_add_u32_e32 v224, v225, v188
	v_cmp_ne_u32_e32 vcc, 0, v174
	s_cbranch_vccz .LBB0_1449
	ds_read_b128 v[64:67], v226
	ds_read_b128 v[128:131], v226 offset:32
	ds_read_b128 v[132:135], v226 offset:64
	ds_read_b128 v[136:139], v226 offset:96
	ds_read_b128 v[140:143], v226 offset:128
	ds_read_b128 v[144:147], v226 offset:160
	ds_read_b128 v[156:159], v226 offset:192
	ds_read_b128 v[228:231], v226 offset:224
	s_waitcnt lgkmcnt(7)
	v_mfma_f32_32x32x16_bf16 v[64:79], v[64:67], v[104:107], 0
	v_add_u32_e32 v148, v224, v198
	v_add_u32_e32 v149, v224, v199
	s_waitcnt lgkmcnt(6)
	v_mfma_f32_32x32x16_bf16 v[64:79], v[128:131], v[80:83], v[64:79]
	v_add_u32_e32 v128, v224, v189
	v_add_u32_e32 v129, v224, v190
	v_add_u32_e32 v130, v224, v191
	v_add_u32_e32 v131, v224, v193
	s_waitcnt lgkmcnt(5)
	v_mfma_f32_32x32x16_bf16 v[64:79], v[132:135], v[84:87], v[64:79]
	ds_read_b64 v[132:133], v128
	ds_read_b64 v[134:135], v129
	ds_read_b64 v[128:129], v130
	ds_read_b64 v[130:131], v131
	s_waitcnt lgkmcnt(8)
	v_mfma_f32_32x32x16_bf16 v[64:79], v[136:139], v[88:91], v[64:79]
	v_add_u32_e32 v136, v224, v194
	v_add_u32_e32 v137, v224, v195
	v_add_u32_e32 v138, v224, v196
	v_add_u32_e32 v139, v224, v197
	s_waitcnt lgkmcnt(7)
	v_mfma_f32_32x32x16_bf16 v[64:79], v[140:143], v[92:95], v[64:79]
	ds_read_b64 v[140:141], v136 offset:5120
	ds_read_b64 v[142:143], v137 offset:5120
	ds_read_b64 v[136:137], v138 offset:5120
	ds_read_b64 v[138:139], v139 offset:5120
	s_waitcnt lgkmcnt(10)
	v_mfma_f32_32x32x16_bf16 v[64:79], v[144:147], v[96:99], v[64:79]
	v_add_u32_e32 v144, v224, v200
	v_add_u32_e32 v145, v224, v201
	ds_read_b64 v[152:153], v148 offset:10240
	ds_read_b64 v[154:155], v149 offset:10240
	ds_read_b64 v[148:149], v144 offset:10240
	ds_read_b64 v[150:151], v145 offset:10240
	v_add_u32_e32 v144, v224, v202
	v_add_u32_e32 v145, v224, v203
	v_add_u32_e32 v146, v224, v204
	v_add_u32_e32 v147, v224, v205
	s_waitcnt lgkmcnt(13)
	v_mfma_f32_32x32x16_bf16 v[64:79], v[156:159], v[100:103], v[64:79]
	ds_read_b64 v[156:157], v144 offset:15360
	ds_read_b64 v[158:159], v145 offset:15360
	ds_read_b64 v[144:145], v146 offset:15360
	ds_read_b64 v[146:147], v147 offset:15360
	s_waitcnt lgkmcnt(14)
	v_mfma_f32_32x32x16_bf16 v[64:79], v[228:231], v[108:111], v[64:79]
	v_lshrrev_b32_e32 v174, v168, v174
	v_and_b32_e32 v227, 1, v174
	s_nop 9
	v_mul_f32_e32 v64, 0x3e0293ee, v64
	v_cmp_eq_u32_e32 vcc, 1, v227
	v_and_b32_e32 v227, 2, v174
	v_mul_f32_e32 v65, 0x3e0293ee, v65
	v_cndmask_b32_e32 v64, v180, v64, vcc
	v_cmp_ne_u32_e32 vcc, 0, v227
	v_and_b32_e32 v228, 4, v174
	v_mul_f32_e32 v66, 0x3e0293ee, v66
	v_cndmask_b32_e32 v65, v180, v65, vcc
	v_cmp_ne_u32_e32 vcc, 0, v228
	v_max3_f32 v227, v64, s82, v65
	v_mul_f32_e32 v68, 0x3e0293ee, v68
	v_cndmask_b32_e32 v228, v180, v66, vcc
	v_mul_f32_e32 v66, 0x3e0293ee, v67
	v_and_b32_e32 v67, 8, v174
	v_cmp_ne_u32_e32 vcc, 0, v67
	s_nop 1
	v_cndmask_b32_e32 v67, v180, v66, vcc
	v_max3_f32 v66, v227, v228, v67
	v_and_b32_e32 v227, 0x100, v174
	v_cmp_ne_u32_e32 vcc, 0, v227
	s_nop 1
	v_cndmask_b32_e32 v227, v180, v68, vcc
	v_mul_f32_e32 v68, 0x3e0293ee, v69
	v_and_b32_e32 v69, 0x200, v174
	v_cmp_ne_u32_e32 vcc, 0, v69
	v_and_b32_e32 v69, 0x400, v174
	s_nop 0
	v_cndmask_b32_e32 v229, v180, v68, vcc
	v_mul_f32_e32 v68, 0x3e0293ee, v70
	v_cmp_ne_u32_e32 vcc, 0, v69
	v_and_b32_e32 v69, 0x800, v174
	v_max3_f32 v66, v66, v227, v229
	v_cndmask_b32_e32 v70, v180, v68, vcc
	v_mul_f32_e32 v68, 0x3e0293ee, v71
	v_cmp_ne_u32_e32 vcc, 0, v69
	v_and_b32_e32 v69, 0x10000, v174
	s_nop 0
	v_cndmask_b32_e32 v230, v180, v68, vcc
	v_mul_f32_e32 v68, 0x3e0293ee, v72
	v_cmp_ne_u32_e32 vcc, 0, v69
	v_and_b32_e32 v69, 0x20000, v174
	v_max3_f32 v66, v66, v70, v230
	v_cndmask_b32_e32 v231, v180, v68, vcc
	v_mul_f32_e32 v68, 0x3e0293ee, v73
	v_cmp_ne_u32_e32 vcc, 0, v69
	v_and_b32_e32 v69, 0x40000, v174
	s_nop 0
	v_cndmask_b32_e32 v73, v180, v68, vcc
	v_mul_f32_e32 v68, 0x3e0293ee, v74
	v_cmp_ne_u32_e32 vcc, 0, v69
	v_and_b32_e32 v69, 0x80000, v174
	v_max3_f32 v66, v66, v231, v73
	v_cndmask_b32_e32 v74, v180, v68, vcc
	v_mul_f32_e32 v68, 0x3e0293ee, v75
	v_cmp_ne_u32_e32 vcc, 0, v69
	v_and_b32_e32 v69, 0x1000000, v174
	s_nop 0
	v_cndmask_b32_e32 v75, v180, v68, vcc
	v_mul_f32_e32 v68, 0x3e0293ee, v76
	v_cmp_ne_u32_e32 vcc, 0, v69
	v_and_b32_e32 v69, 0x2000000, v174
	v_max3_f32 v66, v66, v74, v75
	v_cndmask_b32_e32 v76, v180, v68, vcc
	v_mul_f32_e32 v68, 0x3e0293ee, v77
	v_cmp_ne_u32_e32 vcc, 0, v69
	v_and_b32_e32 v69, 0x4000000, v174
	s_nop 0
	v_cndmask_b32_e32 v232, v180, v68, vcc
	v_mul_f32_e32 v68, 0x3e0293ee, v78
	v_cmp_ne_u32_e32 vcc, 0, v69
	v_and_b32_e32 v69, 0x8000000, v174
	v_max3_f32 v66, v66, v76, v232
	v_cndmask_b32_e32 v233, v180, v68, vcc
	v_mul_f32_e32 v68, 0x3e0293ee, v79
	v_cmp_ne_u32_e32 vcc, 0, v69
	s_nop 1
	v_cndmask_b32_e32 v234, v180, v68, vcc
	v_max3_f32 v66, v66, v233, v234
	ds_bpermute_b32 v68, v186, v66
	s_waitcnt lgkmcnt(0)
	v_max3_f32 v174, v223, v66, v68
	v_sub_f32_e32 v64, v64, v174
	v_exp_f32_e32 v66, v64
	v_sub_f32_e32 v65, v65, v174
	v_exp_f32_e32 v68, v65
	v_sub_f32_e32 v65, v228, v174
	v_exp_f32_e32 v69, v65
	v_sub_f32_e32 v65, v67, v174
	v_exp_f32_e32 v71, v65
	v_sub_f32_e32 v65, v227, v174
	v_add_f32_e32 v77, 0, v66
	v_exp_f32_e32 v72, v65
	v_add_f32_e32 v65, v68, v77
	v_add_f32_e32 v65, v69, v65
	v_add_f32_e32 v65, v71, v65
	v_add_f32_e32 v67, v72, v65
	v_sub_f32_e32 v65, v229, v174
	v_exp_f32_e32 v77, v65
	v_sub_f32_e32 v65, v70, v174
	v_exp_f32_e32 v78, v65
	v_sub_f32_e32 v65, v230, v174
	v_sub_f32_e32 v64, v223, v174
	v_exp_f32_e32 v223, v65
	v_sub_f32_e32 v65, v231, v174
	v_exp_f32_e32 v65, v65
	v_add_f32_e32 v67, v77, v67
	v_add_f32_e32 v67, v78, v67
	v_add_f32_e32 v67, v223, v67
	v_add_f32_e32 v79, v65, v67
	v_sub_f32_e32 v67, v73, v174
	v_exp_f32_e32 v67, v67
	v_sub_f32_e32 v70, v74, v174
	v_exp_f32_e32 v70, v70
	v_sub_f32_e32 v73, v75, v174
	v_exp_f32_e32 v73, v73
	v_sub_f32_e32 v74, v76, v174
	v_exp_f32_e32 v74, v74
	v_sub_f32_e32 v76, v232, v174
	v_add_f32_e32 v75, v67, v79
	v_exp_f32_e32 v79, v76
	v_sub_f32_e32 v76, v233, v174
	v_add_f32_e32 v75, v70, v75
	v_exp_f32_e32 v227, v76
	v_sub_f32_e32 v76, v234, v174
	v_add_f32_e32 v75, v73, v75
	v_exp_f32_e32 v228, v76
	v_add_f32_e32 v75, v74, v75
	v_add_f32_e32 v75, v79, v75
	v_add_f32_e32 v75, v227, v75
	v_add_f32_e32 v75, v228, v75
	v_exp_f32_e32 v64, v64
	ds_bpermute_b32 v76, v186, v75
	v_cmp_neq_f32_e32 vcc, 1.0, v64
	s_cbranch_vccz .LBB0_1445
; __device__ __forceinline__ void dsa_attn_unit(const Ctx& c, int l, int b, int kvh, int qb64) {
;     ...
;             if (__ballot(alpha != 1.0f) != 0ull) {
; #pragma unroll
;                 for (int mt = 0; mt < 4; ++mt)
; #pragma unroll
;                     for (int v = 0; v < 16; ++v) O[mt][v] *= alpha;
;             }
	v_pk_mul_f32 v[62:63], v[62:63], v[64:65] op_sel_hi:[1,0]
	v_pk_mul_f32 v[60:61], v[60:61], v[64:65] op_sel_hi:[1,0]
	v_pk_mul_f32 v[58:59], v[58:59], v[64:65] op_sel_hi:[1,0]
	v_pk_mul_f32 v[56:57], v[56:57], v[64:65] op_sel_hi:[1,0]
	v_pk_mul_f32 v[54:55], v[54:55], v[64:65] op_sel_hi:[1,0]
	v_pk_mul_f32 v[52:53], v[52:53], v[64:65] op_sel_hi:[1,0]
	v_pk_mul_f32 v[50:51], v[50:51], v[64:65] op_sel_hi:[1,0]
	v_pk_mul_f32 v[48:49], v[48:49], v[64:65] op_sel_hi:[1,0]
	v_pk_mul_f32 v[46:47], v[46:47], v[64:65] op_sel_hi:[1,0]
	v_pk_mul_f32 v[44:45], v[44:45], v[64:65] op_sel_hi:[1,0]
	v_pk_mul_f32 v[42:43], v[42:43], v[64:65] op_sel_hi:[1,0]
	v_pk_mul_f32 v[40:41], v[40:41], v[64:65] op_sel_hi:[1,0]
	v_pk_mul_f32 v[38:39], v[38:39], v[64:65] op_sel_hi:[1,0]
	v_pk_mul_f32 v[36:37], v[36:37], v[64:65] op_sel_hi:[1,0]
	v_pk_mul_f32 v[34:35], v[34:35], v[64:65] op_sel_hi:[1,0]
	v_pk_mul_f32 v[32:33], v[32:33], v[64:65] op_sel_hi:[1,0]
	v_pk_mul_f32 v[30:31], v[30:31], v[64:65] op_sel_hi:[1,0]
	v_pk_mul_f32 v[28:29], v[28:29], v[64:65] op_sel_hi:[1,0]
	v_pk_mul_f32 v[26:27], v[26:27], v[64:65] op_sel_hi:[1,0]
	v_pk_mul_f32 v[24:25], v[24:25], v[64:65] op_sel_hi:[1,0]
	v_pk_mul_f32 v[22:23], v[22:23], v[64:65] op_sel_hi:[1,0]
	v_pk_mul_f32 v[20:21], v[20:21], v[64:65] op_sel_hi:[1,0]
	v_pk_mul_f32 v[18:19], v[18:19], v[64:65] op_sel_hi:[1,0]
	v_pk_mul_f32 v[16:17], v[16:17], v[64:65] op_sel_hi:[1,0]
	v_pk_mul_f32 v[14:15], v[14:15], v[64:65] op_sel_hi:[1,0]
	v_pk_mul_f32 v[12:13], v[12:13], v[64:65] op_sel_hi:[1,0]
	v_pk_mul_f32 v[10:11], v[10:11], v[64:65] op_sel_hi:[1,0]
	v_pk_mul_f32 v[8:9], v[8:9], v[64:65] op_sel_hi:[1,0]
	v_pk_mul_f32 v[6:7], v[6:7], v[64:65] op_sel_hi:[1,0]
	v_pk_mul_f32 v[4:5], v[4:5], v[64:65] op_sel_hi:[1,0]
	v_pk_mul_f32 v[2:3], v[2:3], v[64:65] op_sel_hi:[1,0]
	v_pk_mul_f32 v[0:1], v[0:1], v[64:65] op_sel_hi:[1,0]

; #define LAS __attribute__((address_space(3)))
;     template <class T> __device__ __forceinline__ T* w(size_t off) const { return (T*)(pp->ws + off); }
; template <class T> __device__ __forceinline__ LAS T* opq(LAS T* p) { asm volatile("" : "+v"(p)); return p; }
; #define ATT_LOAD(tile) do { _Pragma("unroll") for (int _i = 0; _i < 2; ++_i) { const size_t _o = (size_t)((tile) * 64 + sk0 + 32 * _i) * 256 + sseg * 8; kr[_i] = *(const u32x4*)(KC + _o); vr[_i] = *(const u32x4*)(VC + _o); } } while (0)
; __device__ __forceinline__ void dsa_attn_unit(const Ctx& c, int l, int b, int kvh, int qb64) {
;     const int lane = c.lane, wave = c.wave, n = lane & 31, hf = lane >> 5;
;     const int g = wave >> 1, qh = wave & 1;
;     const int tq = qb64 * 64 + 32 * qh + n, row = b * 2048 + tq, hq = kvh * 4 + g;
;     LAS unsigned char* Kt = opq(c.lds);
;     LAS unsigned char* VT = opq(c.lds + 2 * 64 * 272);
;     const bf16* KC = c.w<bf16>(WS_KC) + (size_t)(b * 2048) * 256 + kvh * 128;
;     const bf16* VC = c.w<bf16>(WS_VC) + (size_t)(b * 2048) * 256 + kvh * 128;
;     const unsigned* mrow = c.w<unsigned>(WS_MASK) + (size_t)row * 64;
;     bf16x8 Qf[8];
;     { const bf16* qp = c.w<bf16>(WS_QC) + (size_t)row * 1024 + hq * 128 + 8 * hf;
; #pragma unroll
;       for (int ks = 0; ks < 8; ++ks) Qf[ks] = *(const bf16x8*)(qp + 16 * ks); }
;     f32x16 O[4];
; #pragma unroll
;     for (int mt = 0; mt < 4; ++mt)
; #pragma unroll
;         for (int v = 0; v < 16; ++v) O[mt][v] = 0.f;
;     float m_run = -1e30f, l_run = 0.f;
;     const int ntile = qb64 + 1;
;     const int sk0 = c.tid >> 4, sseg = c.tid & 15;
;     u32x4 kr[2], vr[2];
;     ...
;     __syncthreads();
;     ATT_LOAD(0); ATT_STORE(0);
; __device__ __forceinline__ void phase_M2(Ctx& c, int l, int q, const XcdBarrier& bar) {
;     if ((int)blockIdx.x < M2_NDP) dscan_unit<0>(c, l, (int)blockIdx.x >> 4, (int)blockIdx.x & 15);
;     for (;;) {
;         const int u = next_unit(c, q);
;         const int pskip = ((int)gridDim.x == 256) ? PRO_NMOD : 0;
;         if (u >= M2_TOTAL + (l == 0 ? PRO_N - pskip : 0)) break;
.LBB0_2884:
	s_or_b64 exec, exec, s[2:3]
	s_waitcnt lgkmcnt(0)
	s_barrier
	ds_read_b32 v0, v176
	s_mov_b64 s[2:3], -1
	s_waitcnt lgkmcnt(0)
	v_readfirstlane_b32 s76, v0
	s_cmpk_gt_i32 s76, 0x19f
	s_cbranch_scc1 .LBB0_2879
	s_cmp_gt_i32 s76, 31
	s_cbranch_scc0 .LBB0_2918
	s_cmpk_gt_u32 s76, 0x9f
	s_cbranch_scc0 .LBB0_2902
	s_add_i32 s2, s76, 0xffffff60
	s_lshr_b32 s6, s2, 3
	s_sub_i32 s8, 31, s6
	s_lshl_b32 s2, s8, 6
	v_mov_b32_e32 v12, v161
	v_mov_b32_e32 v163, s54
	s_or_b32 s7, s2, s39
	s_load_dwordx2 s[2:3], s[90:91], 0xc0
	s_and_b32 s4, s76, 3
	s_lshl_b32 s9, s4, 11
	s_bfe_u32 s5, s76, 0x10002
	s_or_b32 s7, s7, s9
	s_lshl_b32 s16, s4, 20
	v_and_b32_e32 v10, 31, v164
	s_waitcnt lgkmcnt(0)
	s_add_u32 s4, s2, s16
	v_or_b32_e32 v166, s7, v10
	s_addc_u32 s9, s3, 0
	s_lshl_b32 s7, s5, 8
	s_add_u32 s30, s4, s7
	s_addc_u32 s9, s9, 0
	s_add_u32 s10, s30, 0x30100000
	s_addc_u32 s11, s9, 0
	s_lshl_b32 s4, s5, 9
	v_ashrrev_i32_e32 v11, 5, v164
	v_lshlrev_b32_e32 v0, 11, v166
	v_mov_b32_e32 v1, v161
	s_add_i32 s4, s4, s47
	v_lshl_add_u64 v[0:1], s[2:3], 0, v[0:1]
	s_ashr_i32 s5, s4, 31
	v_lshlrev_b32_e32 v2, 3, v11
	v_lshl_add_u64 v[0:1], s[4:5], 1, v[0:1]
	v_ashrrev_i32_e32 v3, 31, v2
	v_lshl_add_u64 v[0:1], v[2:3], 1, v[0:1]
	v_lshl_add_u64 v[2:3], v[0:1], 0, s[18:19]
	v_add_co_u32_e32 v0, vcc, s55, v0
	v_and_b32_e32 v13, 15, v164
	s_nop 0
	v_addc_co_u32_e32 v1, vcc, 0, v1, vcc
	global_load_dwordx4 v[80:83], v[2:3], off offset:32
	global_load_dwordx4 v[84:87], v[2:3], off offset:64
	global_load_dwordx4 v[88:91], v[2:3], off offset:96
	global_load_dwordx4 v[92:95], v[2:3], off offset:128
	global_load_dwordx4 v[96:99], v[2:3], off offset:160
	global_load_dwordx4 v[100:103], v[2:3], off offset:192
	global_load_dwordx4 v[104:107], v[0:1], off
	global_load_dwordx4 v[108:111], v[2:3], off offset:224
	v_ashrrev_i32_e32 v0, 4, v162
	v_ashrrev_i32_e32 v1, 31, v0
	s_add_u32 s30, s30, 0x2fc00000
	v_lshlrev_b32_e32 v14, 4, v13
	v_lshlrev_b64 v[2:3], 9, v[0:1]
	s_addc_u32 s31, s9, 0
	v_or_b32_e32 v4, v2, v14
	v_mov_b32_e32 v5, v3
	v_lshl_add_u64 v[6:7], s[30:31], 0, v[4:5]
	v_lshl_add_u64 v[4:5], s[10:11], 0, v[4:5]
	s_barrier
	global_load_dwordx4 v[112:115], v[6:7], off
	global_load_dwordx4 v[116:119], v[4:5], off
	v_add_u32_e32 v4, 32, v0
	v_ashrrev_i32_e32 v5, 31, v4
	v_lshlrev_b64 v[6:7], 9, v[4:5]
	v_or_b32_e32 v6, v6, v14
	v_lshl_add_u64 v[8:9], s[30:31], 0, v[6:7]
	v_lshl_add_u64 v[6:7], s[10:11], 0, v[6:7]
	global_load_dwordx4 v[120:123], v[8:9], off
	global_load_dwordx4 v[124:127], v[6:7], off
	v_lshlrev_b32_e32 v1, 2, v13
	v_mul_lo_u32 v165, v0, s57
	v_add_u32_e32 v169, v12, v14
	v_mad_u32_u24 v182, v13, s56, v163
	v_xor_b32_e32 v184, v4, v1
	v_xor_b32_e32 v183, v1, v0
	v_add_u32_e32 v0, v169, v165
	v_lshl_add_u32 v4, v184, 1, v182
	v_lshl_add_u32 v1, v183, 1, v182
	v_lshlrev_b32_e32 v168, 2, v11
	v_lshl_add_u64 v[172:173], s[16:17], 0, v[2:3]
	v_mov_b32_e32 v32, v161
	v_mov_b32_e32 v33, v161
	v_mov_b32_e32 v46, v161
	v_mov_b32_e32 v47, v161
	v_lshlrev_b32_e32 v160, 8, v166
	v_lshl_add_u32 v185, v11, 4, v12
	v_mul_u32_u24_e32 v187, 0x110, v10
	v_mul_u32_u24_e32 v188, 0xa0, v10
	v_mad_u32_u24 v209, v10, s59, v179
	v_or3_b32 v172, v172, s7, v14
	v_mov_b32_e32 v34, v161
	v_mov_b32_e32 v35, v161
	v_mov_b32_e32 v36, v161
	v_mov_b32_e32 v37, v161
	v_mov_b32_e32 v38, v161
	v_mov_b32_e32 v39, v161
	v_mov_b32_e32 v40, v161
	v_mov_b32_e32 v41, v161
	v_mov_b32_e32 v42, v161
	v_mov_b32_e32 v43, v161
	v_mov_b32_e32 v44, v161
	v_mov_b32_e32 v45, v161
	v_mov_b64_e32 v[62:63], v[46:47]
	v_mov_b64_e32 v[16:17], v[32:33]
	s_mov_b32 s9, 0
	v_mov_b64_e32 v[170:171], v[160:161]
	v_lshlrev_b32_e32 v160, 10, v166
	s_sub_i32 s10, 32, s6
	v_mov_b32_e32 v213, 0
	v_mov_b32_e32 v223, 0xf149f2ca
	v_mov_b64_e32 v[60:61], v[44:45]
	v_mov_b64_e32 v[58:59], v[42:43]
	v_mov_b64_e32 v[56:57], v[40:41]
	v_mov_b64_e32 v[54:55], v[38:39]
	v_mov_b64_e32 v[52:53], v[36:37]
	v_mov_b64_e32 v[50:51], v[34:35]
	s_waitcnt vmcnt(3)
	ds_write_b128 v0, v[112:115]
	s_waitcnt vmcnt(2)
	ds_write_b16 v1, v116
	ds_write_b16_d16_hi v1, v116 offset:160
	ds_write_b16 v1, v117 offset:320
	ds_write_b16_d16_hi v1, v117 offset:480
	ds_write_b16 v1, v118 offset:640
	ds_write_b16_d16_hi v1, v118 offset:800
	ds_write_b16 v1, v119 offset:960
	ds_write_b16_d16_hi v1, v119 offset:1120
	s_waitcnt vmcnt(1)
	ds_write_b128 v0, v[120:123] offset:8704
	s_waitcnt vmcnt(0)
; #define LAS __attribute__((address_space(3)))
; #define ATT_LOAD(tile) do { _Pragma("unroll") for (int _i = 0; _i < 2; ++_i) { const size_t _o = (size_t)((tile) * 64 + sk0 + 32 * _i) * 256 + sseg * 8; kr[_i] = *(const u32x4*)(KC + _o); vr[_i] = *(const u32x4*)(VC + _o); } } while (0)
; __device__ __forceinline__ void dsa_attn_unit(const Ctx& c, int l, int b, int kvh, int qb64) {
;     ...
;     f32x16 O[4];
; #pragma unroll
;     for (int mt = 0; mt < 4; ++mt)
; #pragma unroll
;         for (int v = 0; v < 16; ++v) O[mt][v] = 0.f;
;     float m_run = -1e30f, l_run = 0.f;
;     const int ntile = qb64 + 1;
;     const int sk0 = c.tid >> 4, sseg = c.tid & 15;
;     u32x4 kr[2], vr[2];
;     ...
;     __syncthreads();
;     ATT_LOAD(0); ATT_STORE(0);
;     __syncthreads();
; #pragma unroll 1
;     for (int it = 0; it < ntile; ++it) {
;         const int bi = it & 1;
;         if (it + 1 < ntile) ATT_LOAD(it + 1);
;         const unsigned mw[2] = {mrow[2 * it], mrow[2 * it + 1]};
; #pragma unroll
;         for (int sub = 0; sub < 2; ++sub) {
;             const unsigned mwd = mw[sub];
;             if (__ballot(mwd != 0u) == 0ull) continue;
;             f32x16 acc;
; #pragma unroll
;             for (int v = 0; v < 16; ++v) acc[v] = 0.f;
;             const LAS unsigned char* kp = Kt + bi * 17408 + (sub * 32 + n) * 272 + hf * 16;
;             bf16x8 Kf[8];
; #pragma unroll
;             for (int ks = 0; ks < 8; ++ks) Kf[ks] = *(const LAS bf16x8*)(kp + ks * 32);
;             __builtin_amdgcn_sched_barrier(0);
; #pragma unroll
;             for (int ks = 0; ks < 8; ++ks) acc = __builtin_amdgcn_mfma_f32_32x32x16_bf16(Kf[ks], Qf[ks], acc, 0, 0, 0);
;             bf16x8 Vf[8];
; #pragma unroll
;             for (int mt = 0; mt < 4; ++mt)
; #pragma unroll
;                 for (int s2 = 0; s2 < 2; ++s2) {
;                     const int xr = 4 * (4 * mt + (n >> 3)), kb = sub * 32 + 16 * s2 + 4 * hf;
;                     const LAS unsigned char* vrow = VT + bi * 20480 + (32 * mt + n) * 160;
;                     const u32x2 lo = *(const LAS u32x2*)(vrow + (kb ^ xr) * 2), hi = *(const LAS u32x2*)(vrow + ((kb + 8) ^ xr) * 2);
;     ...
;         if (it + 1 < ntile) ATT_STORE(bi ^ 1);
;         __syncthreads();
;     }
	ds_write_b16 v4, v124
	ds_write_b16_d16_hi v4, v124 offset:160
	ds_write_b16 v4, v125 offset:320
	ds_write_b16_d16_hi v4, v125 offset:480
	ds_write_b16 v4, v126 offset:640
	ds_write_b16_d16_hi v4, v126 offset:800
	ds_write_b16 v4, v127 offset:960
	ds_write_b16_d16_hi v4, v127 offset:1120
	v_lshrrev_b32_e32 v0, 1, v164
	v_lshlrev_b32_e32 v4, 2, v164
	v_xor_b32_e32 v186, 0x80, v4
	v_bitop3_b32 v4, v168, v0, 12 bitop3:0x78
	v_lshlrev_b32_e32 v189, 1, v4
	v_add_u32_e32 v4, 8, v168
	v_bitop3_b32 v5, v4, v0, 12 bitop3:0x78
	v_lshlrev_b32_e32 v190, 1, v5
	v_add_u32_e32 v5, 16, v168
	v_bitop3_b32 v6, v5, v0, 12 bitop3:0x78
	v_lshlrev_b32_e32 v191, 1, v6
	v_add_u32_e32 v6, 24, v168
	v_and_b32_e32 v1, 12, v0
	v_bitop3_b32 v7, v6, v0, 12 bitop3:0x78
	v_lshlrev_b32_e32 v192, 1, v7
	v_bitop3_b32 v7, v1, v168, 16 bitop3:0x36
	v_lshlrev_b32_e32 v193, 1, v7
	v_bitop3_b32 v7, v4, v1, 16 bitop3:0x1e
	v_lshlrev_b32_e32 v194, 1, v7
	v_bitop3_b32 v7, v5, v1, 16 bitop3:0x1e
	v_lshlrev_b32_e32 v195, 1, v7
	v_bitop3_b32 v7, v6, v1, 16 bitop3:0x1e
	v_lshlrev_b32_e32 v196, 1, v7
	v_bitop3_b32 v7, v1, v168, 32 bitop3:0x36
	v_lshlrev_b32_e32 v197, 1, v7
	v_bitop3_b32 v7, v4, v1, 32 bitop3:0x1e
	v_bitop3_b32 v4, v4, v1, 48 bitop3:0x1e
	v_lshlrev_b32_e32 v202, 1, v4
	v_bitop3_b32 v4, v5, v1, 48 bitop3:0x1e
	v_lshlrev_b32_e32 v203, 1, v4
	v_bitop3_b32 v4, v6, v1, 48 bitop3:0x1e
	v_lshlrev_b32_e32 v204, 1, v4
	v_add_u32_e32 v4, 32, v168
	v_lshlrev_b32_e32 v198, 1, v7
	v_bitop3_b32 v7, v5, v1, 32 bitop3:0x1e
	v_bitop3_b32 v5, v4, v0, 12 bitop3:0x78
	v_lshlrev_b32_e32 v205, 1, v5
	v_add_u32_e32 v5, 40, v168
	v_lshlrev_b32_e32 v199, 1, v7
	v_bitop3_b32 v7, v6, v1, 32 bitop3:0x1e
	v_bitop3_b32 v6, v5, v0, 12 bitop3:0x78
	v_lshlrev_b32_e32 v200, 1, v7
	v_bitop3_b32 v7, v1, v168, 48 bitop3:0x36
	v_lshlrev_b32_e32 v206, 1, v6
	v_add_u32_e32 v6, 48, v168
	v_lshlrev_b32_e32 v201, 1, v7
	v_bitop3_b32 v7, v6, v0, 12 bitop3:0x78
	v_lshlrev_b32_e32 v207, 1, v7
	v_add_u32_e32 v7, 56, v168
	v_bitop3_b32 v0, v7, v0, 12 bitop3:0x78
	v_lshlrev_b32_e32 v208, 1, v0
	v_bitop3_b32 v0, v4, v1, 16 bitop3:0x1e
	v_lshlrev_b32_e32 v210, 1, v0
	v_bitop3_b32 v0, v5, v1, 16 bitop3:0x1e
	v_lshlrev_b32_e32 v211, 1, v0
	v_bitop3_b32 v0, v6, v1, 16 bitop3:0x1e
	v_lshlrev_b32_e32 v212, 1, v0
	v_bitop3_b32 v0, v7, v1, 16 bitop3:0x1e
	v_lshlrev_b32_e32 v214, 1, v0
	v_bitop3_b32 v0, v4, v1, 32 bitop3:0x1e
	v_lshlrev_b32_e32 v215, 1, v0
	v_bitop3_b32 v0, v5, v1, 32 bitop3:0x1e
	v_lshlrev_b32_e32 v216, 1, v0
	v_bitop3_b32 v0, v6, v1, 32 bitop3:0x1e
	v_lshlrev_b32_e32 v217, 1, v0
	v_bitop3_b32 v0, v7, v1, 32 bitop3:0x1e
	v_lshlrev_b32_e32 v218, 1, v0
	v_bitop3_b32 v0, v4, v1, 48 bitop3:0x1e
	v_lshlrev_b32_e32 v219, 1, v0
	v_bitop3_b32 v0, v5, v1, 48 bitop3:0x1e
	v_lshlrev_b32_e32 v220, 1, v0
	v_bitop3_b32 v0, v6, v1, 48 bitop3:0x1e
	v_lshlrev_b32_e32 v221, 1, v0
	v_bitop3_b32 v0, v7, v1, 48 bitop3:0x1e
	v_lshlrev_b32_e32 v222, 1, v0
	v_mov_b64_e32 v[0:1], v[32:33]
	v_mov_b64_e32 v[48:49], v[32:33]
	v_mov_b64_e32 v[18:19], v[34:35]
	v_mov_b64_e32 v[20:21], v[36:37]
	v_mov_b64_e32 v[22:23], v[38:39]
	v_mov_b64_e32 v[24:25], v[40:41]
	v_mov_b64_e32 v[26:27], v[42:43]
	v_mov_b64_e32 v[28:29], v[44:45]
	v_mov_b64_e32 v[30:31], v[46:47]
	v_mov_b64_e32 v[2:3], v[34:35]
	v_mov_b64_e32 v[4:5], v[36:37]
	v_mov_b64_e32 v[6:7], v[38:39]
	v_mov_b64_e32 v[8:9], v[40:41]
	v_mov_b64_e32 v[10:11], v[42:43]
	v_mov_b64_e32 v[12:13], v[44:45]
	v_mov_b64_e32 v[14:15], v[46:47]
	s_waitcnt lgkmcnt(0)
	s_barrier
	v_lshl_add_u64 v[64:65], s[2:3], 0, v[170:171]
	v_add_co_u32_e32 v64, vcc, 0x4b800000, v64
	s_nop 1
	v_addc_co_u32_e32 v65, vcc, 0, v65, vcc
	global_load_dwordx2 v[174:175], v[64:65], off
	s_branch .LBB0_2890
.LBB0_2888:
	s_waitcnt vmcnt(0)
	s_xor_b32 s6, s11, 1
	s_mul_i32 s7, s6, 0x4400
	s_mulk_i32 s6, 0x5000
	v_add_u32_e32 v64, s6, v182
	v_add3_u32 v65, v169, s7, v165
	v_lshl_add_u32 v66, v183, 1, v64
	v_lshl_add_u32 v64, v184, 1, v64
	ds_write_b128 v65, v[112:115]
	ds_write_b16 v66, v116
	ds_write_b16_d16_hi v66, v116 offset:160
	ds_write_b16 v66, v117 offset:320
	ds_write_b16_d16_hi v66, v117 offset:480
	ds_write_b16 v66, v118 offset:640
	ds_write_b16_d16_hi v66, v118 offset:800
	ds_write_b16 v66, v119 offset:960
	ds_write_b16_d16_hi v66, v119 offset:1120
	ds_write_b128 v65, v[120:123] offset:8704
	ds_write_b16 v64, v124
	ds_write_b16_d16_hi v64, v124 offset:160
	ds_write_b16 v64, v125 offset:320
	ds_write_b16_d16_hi v64, v125 offset:480
	ds_write_b16 v64, v126 offset:640
	ds_write_b16_d16_hi v64, v126 offset:800
	ds_write_b16 v64, v127 offset:960
	ds_write_b16_d16_hi v64, v127 offset:1120
.LBB0_2889:
	s_waitcnt vmcnt(0)
	v_mov_b32_e32 v174, v236
	v_mov_b32_e32 v175, v237
	s_add_i32 s9, s9, 1
	v_lshl_add_u64 v[170:171], v[170:171], 0, 8
	s_cmp_lg_u32 s10, s9
	v_lshl_add_u64 v[172:173], v[172:173], 0, s[20:21]
	s_waitcnt lgkmcnt(0)
	s_barrier
	s_cbranch_scc0 .LBB0_2901
.LBB0_2890:
	v_lshl_add_u64 v[64:65], s[2:3], 0, v[170:171]
	v_add_co_u32_e32 v64, vcc, 0x4b800000, v64
	s_nop 1
	v_addc_co_u32_e32 v65, vcc, 0, v65, vcc
	global_load_dwordx2 v[236:237], v[64:65], off offset:8
	s_cmp_lt_u32 s9, s8
	s_cselect_b64 s[6:7], -1, 0
	s_cmp_ge_u32 s9, s8
	s_cbranch_scc1 .La1_nonext
	v_lshl_add_u64 v[64:65], s[2:3], 0, v[172:173]
	v_add_co_u32_e32 v66, vcc, 0x2fc08000, v64
	s_nop 1
	v_addc_co_u32_e32 v67, vcc, 0, v65, vcc
	v_add_co_u32_e32 v68, vcc, 0x30108000, v64
	s_nop 1
	v_addc_co_u32_e32 v69, vcc, 0, v65, vcc
	global_load_dwordx4 v[112:115], v[66:67], off
	global_load_dwordx4 v[116:119], v[68:69], off
	v_add_co_u32_e32 v66, vcc, 0x2fc0c000, v64
	s_nop 1
	v_addc_co_u32_e32 v67, vcc, 0, v65, vcc
	v_add_co_u32_e32 v64, vcc, 0x3010c000, v64
	s_nop 1
	v_addc_co_u32_e32 v65, vcc, 0, v65, vcc
	global_load_dwordx4 v[120:123], v[66:67], off
	global_load_dwordx4 v[124:127], v[64:65], off
	s_waitcnt vmcnt(5)
	s_branch .LBB0_2892

; #define LAS __attribute__((address_space(3)))
; __device__ __forceinline__ void dsa_attn_unit(const Ctx& c, int l, int b, int kvh, int qb64) {
;     ...
;             const unsigned mwd = mw[sub];
;             if (__ballot(mwd != 0u) == 0ull) continue;
;             f32x16 acc;
; #pragma unroll
;             for (int v = 0; v < 16; ++v) acc[v] = 0.f;
;             const LAS unsigned char* kp = Kt + bi * 17408 + (sub * 32 + n) * 272 + hf * 16;
;             bf16x8 Kf[8];
; #pragma unroll
;             for (int ks = 0; ks < 8; ++ks) Kf[ks] = *(const LAS bf16x8*)(kp + ks * 32);
;             __builtin_amdgcn_sched_barrier(0);
; #pragma unroll
;             for (int ks = 0; ks < 8; ++ks) acc = __builtin_amdgcn_mfma_f32_32x32x16_bf16(Kf[ks], Qf[ks], acc, 0, 0, 0);
;             bf16x8 Vf[8];
; #pragma unroll
;             for (int mt = 0; mt < 4; ++mt)
; #pragma unroll
;                 for (int s2 = 0; s2 < 2; ++s2) {
;                     const int xr = 4 * (4 * mt + (n >> 3)), kb = sub * 32 + 16 * s2 + 4 * hf;
;                     const LAS unsigned char* vrow = VT + bi * 20480 + (32 * mt + n) * 160;
;                     const u32x2 lo = *(const LAS u32x2*)(vrow + (kb ^ xr) * 2), hi = *(const LAS u32x2*)(vrow + ((kb + 8) ^ xr) * 2);
;                     const u32x4 t = {lo.x, lo.y, hi.x, hi.y};
;                     Vf[mt * 2 + s2] = __builtin_bit_cast(bf16x8, t);
;                 }
;             __builtin_amdgcn_sched_barrier(0);
;             const unsigned wsh = mwd >> (4 * hf);
;             float mx = -INFINITY;
; #pragma unroll
;             for (int v = 0; v < 16; ++v) { const bool selv = (wsh >> ((v & 3) + 8 * (v >> 2))) & 1u; acc[v] = selv ? acc[v] * 0.12751743f : -INFINITY; mx = fmaxf(mx, acc[v]); }
;             mx = fmaxf(mx, lane_get(mx, lane ^ 32));
;             const float m_new = fmaxf(m_run, mx);
;             const float alpha = __builtin_amdgcn_exp2f(m_run - m_new);
;             float rs = 0.f;
; #pragma unroll
;             for (int v = 0; v < 16; ++v) { acc[v] = __builtin_amdgcn_exp2f(acc[v] - m_new); rs += acc[v]; }
;             rs += lane_get(rs, lane ^ 32);
;             l_run = l_run * alpha + rs; m_run = m_new;
;             if (__ballot(alpha != 1.0f) != 0ull) {
.LBB0_2892:
	s_and_b32 s11, s9, 1
	s_mul_i32 s16, s11, 0x4400
	s_mul_i32 s30, s11, 0x5000
	v_add_u32_e32 v64, s16, v185
	v_add_u32_e32 v225, s30, v163
	v_add_u32_e32 v226, v64, v187
	v_add_u32_e32 v224, v225, v188
	v_cmp_ne_u32_e32 vcc, 0, v174
	s_cbranch_vccz .LBB0_2899
	ds_read_b128 v[64:67], v226
	ds_read_b128 v[128:131], v226 offset:32
	ds_read_b128 v[132:135], v226 offset:64
	ds_read_b128 v[136:139], v226 offset:96
	ds_read_b128 v[140:143], v226 offset:128
	ds_read_b128 v[144:147], v226 offset:160
	ds_read_b128 v[156:159], v226 offset:192
	ds_read_b128 v[228:231], v226 offset:224
	s_waitcnt lgkmcnt(7)
	v_mfma_f32_32x32x16_bf16 v[64:79], v[64:67], v[104:107], 0
	v_add_u32_e32 v148, v224, v197
	v_add_u32_e32 v149, v224, v198
	s_waitcnt lgkmcnt(6)
	v_mfma_f32_32x32x16_bf16 v[64:79], v[128:131], v[80:83], v[64:79]
	v_add_u32_e32 v128, v224, v189
	v_add_u32_e32 v129, v224, v190
	v_add_u32_e32 v130, v224, v191
	v_add_u32_e32 v131, v224, v192
	s_waitcnt lgkmcnt(5)
	v_mfma_f32_32x32x16_bf16 v[64:79], v[132:135], v[84:87], v[64:79]
	ds_read_b64 v[132:133], v128
	ds_read_b64 v[134:135], v129
	ds_read_b64 v[128:129], v130
	ds_read_b64 v[130:131], v131
	s_waitcnt lgkmcnt(8)
	v_mfma_f32_32x32x16_bf16 v[64:79], v[136:139], v[88:91], v[64:79]
	v_add_u32_e32 v136, v224, v193
	v_add_u32_e32 v137, v224, v194
	v_add_u32_e32 v138, v224, v195
	v_add_u32_e32 v139, v224, v196
	s_waitcnt lgkmcnt(7)
	v_mfma_f32_32x32x16_bf16 v[64:79], v[140:143], v[92:95], v[64:79]
	ds_read_b64 v[140:141], v136 offset:5120
	ds_read_b64 v[142:143], v137 offset:5120
	ds_read_b64 v[136:137], v138 offset:5120
	ds_read_b64 v[138:139], v139 offset:5120
	s_waitcnt lgkmcnt(10)
	v_mfma_f32_32x32x16_bf16 v[64:79], v[144:147], v[96:99], v[64:79]
	v_add_u32_e32 v144, v224, v199
	v_add_u32_e32 v145, v224, v200
	ds_read_b64 v[152:153], v148 offset:10240
	ds_read_b64 v[154:155], v149 offset:10240
	ds_read_b64 v[148:149], v144 offset:10240
	ds_read_b64 v[150:151], v145 offset:10240
	v_add_u32_e32 v144, v224, v201
	v_add_u32_e32 v145, v224, v202
	v_add_u32_e32 v146, v224, v203
	v_add_u32_e32 v147, v224, v204
	s_waitcnt lgkmcnt(13)
	v_mfma_f32_32x32x16_bf16 v[64:79], v[156:159], v[100:103], v[64:79]
	ds_read_b64 v[156:157], v144 offset:15360
	ds_read_b64 v[158:159], v145 offset:15360
	ds_read_b64 v[144:145], v146 offset:15360
	ds_read_b64 v[146:147], v147 offset:15360
	s_waitcnt lgkmcnt(14)
	v_mfma_f32_32x32x16_bf16 v[64:79], v[228:231], v[108:111], v[64:79]
	v_lshrrev_b32_e32 v174, v168, v174
	v_and_b32_e32 v227, 1, v174
	s_nop 9
	v_mul_f32_e32 v64, 0x3e0293ee, v64
	v_cmp_eq_u32_e32 vcc, 1, v227
	v_and_b32_e32 v227, 2, v174
	v_mul_f32_e32 v65, 0x3e0293ee, v65
	v_cndmask_b32_e32 v64, v180, v64, vcc
	v_cmp_ne_u32_e32 vcc, 0, v227
	v_and_b32_e32 v228, 4, v174
	v_mul_f32_e32 v66, 0x3e0293ee, v66
	v_cndmask_b32_e32 v65, v180, v65, vcc
	v_cmp_ne_u32_e32 vcc, 0, v228
	v_max3_f32 v227, v64, s60, v65
	v_mul_f32_e32 v68, 0x3e0293ee, v68
	v_cndmask_b32_e32 v228, v180, v66, vcc
	v_mul_f32_e32 v66, 0x3e0293ee, v67
	v_and_b32_e32 v67, 8, v174
	v_cmp_ne_u32_e32 vcc, 0, v67
	s_nop 1
	v_cndmask_b32_e32 v67, v180, v66, vcc
	v_max3_f32 v66, v227, v228, v67
	v_and_b32_e32 v227, 0x100, v174
	v_cmp_ne_u32_e32 vcc, 0, v227
	s_nop 1
	v_cndmask_b32_e32 v227, v180, v68, vcc
	v_mul_f32_e32 v68, 0x3e0293ee, v69
	v_and_b32_e32 v69, 0x200, v174
	v_cmp_ne_u32_e32 vcc, 0, v69
	v_and_b32_e32 v69, 0x400, v174
	s_nop 0
	v_cndmask_b32_e32 v229, v180, v68, vcc
	v_mul_f32_e32 v68, 0x3e0293ee, v70
	v_cmp_ne_u32_e32 vcc, 0, v69
	v_and_b32_e32 v69, 0x800, v174
	v_max3_f32 v66, v66, v227, v229
	v_cndmask_b32_e32 v70, v180, v68, vcc
	v_mul_f32_e32 v68, 0x3e0293ee, v71
	v_cmp_ne_u32_e32 vcc, 0, v69
	v_and_b32_e32 v69, 0x10000, v174
	s_nop 0
	v_cndmask_b32_e32 v230, v180, v68, vcc
	v_mul_f32_e32 v68, 0x3e0293ee, v72
	v_cmp_ne_u32_e32 vcc, 0, v69
	v_and_b32_e32 v69, 0x20000, v174
	v_max3_f32 v66, v66, v70, v230
	v_cndmask_b32_e32 v231, v180, v68, vcc
	v_mul_f32_e32 v68, 0x3e0293ee, v73
	v_cmp_ne_u32_e32 vcc, 0, v69
	v_and_b32_e32 v69, 0x40000, v174
	s_nop 0
	v_cndmask_b32_e32 v73, v180, v68, vcc
	v_mul_f32_e32 v68, 0x3e0293ee, v74
	v_cmp_ne_u32_e32 vcc, 0, v69
	v_and_b32_e32 v69, 0x80000, v174
	v_max3_f32 v66, v66, v231, v73
	v_cndmask_b32_e32 v74, v180, v68, vcc
	v_mul_f32_e32 v68, 0x3e0293ee, v75
	v_cmp_ne_u32_e32 vcc, 0, v69
	v_and_b32_e32 v69, 0x1000000, v174
	s_nop 0
	v_cndmask_b32_e32 v75, v180, v68, vcc
	v_mul_f32_e32 v68, 0x3e0293ee, v76
	v_cmp_ne_u32_e32 vcc, 0, v69
	v_and_b32_e32 v69, 0x2000000, v174
	v_max3_f32 v66, v66, v74, v75
	v_cndmask_b32_e32 v76, v180, v68, vcc
	v_mul_f32_e32 v68, 0x3e0293ee, v77
	v_cmp_ne_u32_e32 vcc, 0, v69
	v_and_b32_e32 v69, 0x4000000, v174
	s_nop 0
	v_cndmask_b32_e32 v232, v180, v68, vcc
	v_mul_f32_e32 v68, 0x3e0293ee, v78
	v_cmp_ne_u32_e32 vcc, 0, v69
	v_and_b32_e32 v69, 0x8000000, v174
	v_max3_f32 v66, v66, v76, v232
	v_cndmask_b32_e32 v233, v180, v68, vcc
	v_mul_f32_e32 v68, 0x3e0293ee, v79
	v_cmp_ne_u32_e32 vcc, 0, v69
	s_nop 1
	v_cndmask_b32_e32 v234, v180, v68, vcc
	v_max3_f32 v66, v66, v233, v234
	ds_bpermute_b32 v68, v186, v66
	s_waitcnt lgkmcnt(0)
	v_max3_f32 v174, v223, v66, v68
	v_sub_f32_e32 v64, v64, v174
	v_exp_f32_e32 v66, v64
	v_sub_f32_e32 v65, v65, v174
	v_exp_f32_e32 v68, v65
	v_sub_f32_e32 v65, v228, v174
	v_exp_f32_e32 v69, v65
	v_sub_f32_e32 v65, v67, v174
	v_exp_f32_e32 v71, v65
	v_sub_f32_e32 v65, v227, v174
	v_add_f32_e32 v77, 0, v66
	v_exp_f32_e32 v72, v65
	v_add_f32_e32 v65, v68, v77
	v_add_f32_e32 v65, v69, v65
	v_add_f32_e32 v65, v71, v65
	v_add_f32_e32 v67, v72, v65
	v_sub_f32_e32 v65, v229, v174
	v_exp_f32_e32 v77, v65
	v_sub_f32_e32 v65, v70, v174
	v_exp_f32_e32 v78, v65
	v_sub_f32_e32 v65, v230, v174
	v_sub_f32_e32 v64, v223, v174
	v_exp_f32_e32 v223, v65
	v_sub_f32_e32 v65, v231, v174
	v_exp_f32_e32 v65, v65
	v_add_f32_e32 v67, v77, v67
	v_add_f32_e32 v67, v78, v67
	v_add_f32_e32 v67, v223, v67
	v_add_f32_e32 v79, v65, v67
	v_sub_f32_e32 v67, v73, v174
	v_exp_f32_e32 v67, v67
	v_sub_f32_e32 v70, v74, v174
	v_exp_f32_e32 v70, v70
	v_sub_f32_e32 v73, v75, v174
	v_exp_f32_e32 v73, v73
	v_sub_f32_e32 v74, v76, v174
	v_exp_f32_e32 v74, v74
	v_sub_f32_e32 v76, v232, v174
	v_add_f32_e32 v75, v67, v79
	v_exp_f32_e32 v79, v76
	v_sub_f32_e32 v76, v233, v174
	v_add_f32_e32 v75, v70, v75
	v_exp_f32_e32 v227, v76
	v_sub_f32_e32 v76, v234, v174
	v_add_f32_e32 v75, v73, v75
	v_exp_f32_e32 v228, v76
	v_add_f32_e32 v75, v74, v75
	v_add_f32_e32 v75, v79, v75
	v_add_f32_e32 v75, v227, v75
	v_add_f32_e32 v75, v228, v75
	v_exp_f32_e32 v64, v64
	ds_bpermute_b32 v76, v186, v75
	v_cmp_neq_f32_e32 vcc, 1.0, v64
	s_cbranch_vccz .LBB0_2895
; __device__ __forceinline__ void dsa_attn_unit(const Ctx& c, int l, int b, int kvh, int qb64) {
;     ...
;             if (__ballot(alpha != 1.0f) != 0ull) {
; #pragma unroll
;                 for (int mt = 0; mt < 4; ++mt)
; #pragma unroll
;                     for (int v = 0; v < 16; ++v) O[mt][v] *= alpha;
;             }
	v_pk_mul_f32 v[62:63], v[62:63], v[64:65] op_sel_hi:[1,0]
	v_pk_mul_f32 v[60:61], v[60:61], v[64:65] op_sel_hi:[1,0]
	v_pk_mul_f32 v[58:59], v[58:59], v[64:65] op_sel_hi:[1,0]
	v_pk_mul_f32 v[56:57], v[56:57], v[64:65] op_sel_hi:[1,0]
	v_pk_mul_f32 v[54:55], v[54:55], v[64:65] op_sel_hi:[1,0]
	v_pk_mul_f32 v[52:53], v[52:53], v[64:65] op_sel_hi:[1,0]
	v_pk_mul_f32 v[50:51], v[50:51], v[64:65] op_sel_hi:[1,0]
	v_pk_mul_f32 v[48:49], v[48:49], v[64:65] op_sel_hi:[1,0]
	v_pk_mul_f32 v[46:47], v[46:47], v[64:65] op_sel_hi:[1,0]
	v_pk_mul_f32 v[44:45], v[44:45], v[64:65] op_sel_hi:[1,0]
	v_pk_mul_f32 v[42:43], v[42:43], v[64:65] op_sel_hi:[1,0]
	v_pk_mul_f32 v[40:41], v[40:41], v[64:65] op_sel_hi:[1,0]
	v_pk_mul_f32 v[38:39], v[38:39], v[64:65] op_sel_hi:[1,0]
	v_pk_mul_f32 v[36:37], v[36:37], v[64:65] op_sel_hi:[1,0]
	v_pk_mul_f32 v[34:35], v[34:35], v[64:65] op_sel_hi:[1,0]
	v_pk_mul_f32 v[32:33], v[32:33], v[64:65] op_sel_hi:[1,0]
	v_pk_mul_f32 v[30:31], v[30:31], v[64:65] op_sel_hi:[1,0]
	v_pk_mul_f32 v[28:29], v[28:29], v[64:65] op_sel_hi:[1,0]
	v_pk_mul_f32 v[26:27], v[26:27], v[64:65] op_sel_hi:[1,0]
	v_pk_mul_f32 v[24:25], v[24:25], v[64:65] op_sel_hi:[1,0]
	v_pk_mul_f32 v[22:23], v[22:23], v[64:65] op_sel_hi:[1,0]
	v_pk_mul_f32 v[20:21], v[20:21], v[64:65] op_sel_hi:[1,0]
	v_pk_mul_f32 v[18:19], v[18:19], v[64:65] op_sel_hi:[1,0]
	v_pk_mul_f32 v[16:17], v[16:17], v[64:65] op_sel_hi:[1,0]
	v_pk_mul_f32 v[14:15], v[14:15], v[64:65] op_sel_hi:[1,0]
	v_pk_mul_f32 v[12:13], v[12:13], v[64:65] op_sel_hi:[1,0]
	v_pk_mul_f32 v[10:11], v[10:11], v[64:65] op_sel_hi:[1,0]
	v_pk_mul_f32 v[8:9], v[8:9], v[64:65] op_sel_hi:[1,0]
	v_pk_mul_f32 v[6:7], v[6:7], v[64:65] op_sel_hi:[1,0]
	v_pk_mul_f32 v[4:5], v[4:5], v[64:65] op_sel_hi:[1,0]
	v_pk_mul_f32 v[2:3], v[2:3], v[64:65] op_sel_hi:[1,0]
	v_pk_mul_f32 v[0:1], v[0:1], v[64:65] op_sel_hi:[1,0]
